# instruction prefetch at seams: while waiting at each seam one wave touches the next 8-64 KB of code (the next phase's instructions) so the phase-start instruction-cache misses are served from L2; on t
# speedup vs baseline: 1.0259x; 1.0062x over previous
.LBB0_25:
	s_cmp_gt_i32 s95, 1
	s_cselect_b64 s[4:5], -1, 0
	s_and_b64 s[2:3], s[46:47], s[4:5]
	s_andn2_b64 vcc, exec, s[2:3]
	s_cbranch_vccnz .LBB0_75
	s_waitcnt vmcnt(0)
	v_cmp_eq_u32_e32 vcc, 0, v0
	s_barrier
	v_lshrrev_b32_e32 v1, 6, v0
	v_and_b32_e32 v2, 63, v0
	v_cmp_eq_u32_e32 vcc, 5, v1
	s_and_saveexec_b64 s[8:9], vcc
	s_cbranch_execz .Lipf0
	s_getpc_b64 s[2:3]
	v_lshlrev_b32_e32 v1, 7, v2
	global_load_dword v3, v1, s[2:3]
	s_add_u32 s2, s2, 0x2000
	s_addc_u32 s3, s3, 0
	global_load_dword v3, v1, s[2:3]
	s_add_u32 s2, s2, 0x2000
	s_addc_u32 s3, s3, 0
	global_load_dword v3, v1, s[2:3]
	s_add_u32 s2, s2, 0x2000
	s_addc_u32 s3, s3, 0
	global_load_dword v3, v1, s[2:3]
	s_add_u32 s2, s2, 0x2000
	s_addc_u32 s3, s3, 0
	global_load_dword v3, v1, s[2:3]
	s_add_u32 s2, s2, 0x2000
	s_addc_u32 s3, s3, 0
	global_load_dword v3, v1, s[2:3]
	s_add_u32 s2, s2, 0x2000
	s_addc_u32 s3, s3, 0
	global_load_dword v3, v1, s[2:3]
	s_add_u32 s2, s2, 0x2000
	s_addc_u32 s3, s3, 0
	global_load_dword v3, v1, s[2:3]
.Lipf0:
	s_or_b64 exec, exec, s[8:9]
	v_cmp_eq_u32_e32 vcc, 0, v0
	s_and_saveexec_b64 s[6:7], vcc
	s_cbranch_execz .LBB0_74
	v_readlane_b32 s2, v253, 3
	s_waitcnt vmcnt(0) expcnt(0) lgkmcnt(0)
	s_nop 0
	v_mov_b32_e32 v1, s2
	ds_read_b32 v3, v1
	ds_read_b32 v1, v1 offset:4
	s_waitcnt lgkmcnt(1)
	v_cmp_ne_u32_e32 vcc, 0, v3
	s_cbranch_vccnz .LBB0_42
	v_readlane_b32 s8, v253, 0
	v_readlane_b32 s9, v253, 1
	s_load_dwordx2 s[2:3], s[8:9], 0x4
	s_add_u32 s8, s44, 0x1200
	s_addc_u32 s9, s45, 0
	s_add_u32 s10, s44, 0x1400
	s_addc_u32 s11, s45, 0
	s_add_u32 s12, s44, 0x1500
	s_addc_u32 s13, s45, 0
	s_add_u32 s14, s44, 0x1600
	s_addc_u32 s15, s45, 0
	s_add_u32 s16, s44, 0x1700
	s_addc_u32 s17, s45, 0
	s_add_u32 s18, s44, 0x1800
	s_addc_u32 s19, s45, 0
	s_add_u32 s20, s44, 0x1900
	s_addc_u32 s21, s45, 0
	s_add_u32 s22, s44, 0x1a00
	s_addc_u32 s23, s45, 0
	s_add_u32 s24, s44, 0x1b00
	s_addc_u32 s25, s45, 0
	s_add_u32 s26, s44, 0x1c00
	s_addc_u32 s27, s45, 0
	s_add_u32 s28, s44, 0x1d00
	s_addc_u32 s29, s45, 0
	s_add_u32 s30, s44, 0x1e00
	s_addc_u32 s31, s45, 0
	s_add_u32 s34, s44, 0x1f00
	s_addc_u32 s35, s45, 0
	s_add_u32 s36, s44, 0x2000
	s_addc_u32 s37, s45, 0
	s_add_u32 s38, s44, 0x2100
	s_addc_u32 s39, s45, 0
	s_add_u32 s40, s44, 0x2200
	s_addc_u32 s41, s45, 0
	s_waitcnt lgkmcnt(0)
	s_mul_i32 s2, s2, s96
	s_add_u32 s42, s44, 0x2300
	s_mul_i32 s2, s2, s3
	s_addc_u32 s43, s45, 0
	s_mov_b32 s3, 1
	v_mov_b32_e32 v17, 0
	s_branch .LBB0_30

.LBB0_112:
	s_cmp_gt_i32 s95, 2
	s_cselect_b64 s[4:5], -1, 0
	s_and_b64 s[0:1], s[12:13], s[4:5]
	s_and_b64 vcc, exec, s[0:1]
	s_cbranch_vccz .LBB0_162
	s_waitcnt vmcnt(0)
	v_cmp_eq_u32_e32 vcc, 0, v0
	s_waitcnt lgkmcnt(0)
	s_barrier
	v_lshrrev_b32_e32 v1, 6, v0
	v_and_b32_e32 v2, 63, v0
	v_cmp_eq_u32_e32 vcc, 5, v1
	s_and_saveexec_b64 s[8:9], vcc
	s_cbranch_execz .Lipf1
	s_getpc_b64 s[2:3]
	v_lshlrev_b32_e32 v1, 7, v2
	global_load_dword v3, v1, s[2:3]
	s_add_u32 s2, s2, 0x2000
	s_addc_u32 s3, s3, 0
	global_load_dword v3, v1, s[2:3]
	s_add_u32 s2, s2, 0x2000
	s_addc_u32 s3, s3, 0
	global_load_dword v3, v1, s[2:3]
	s_add_u32 s2, s2, 0x2000
	s_addc_u32 s3, s3, 0
	global_load_dword v3, v1, s[2:3]
	s_add_u32 s2, s2, 0x2000
	s_addc_u32 s3, s3, 0
	global_load_dword v3, v1, s[2:3]
	s_add_u32 s2, s2, 0x2000
	s_addc_u32 s3, s3, 0
	global_load_dword v3, v1, s[2:3]
	s_add_u32 s2, s2, 0x2000
	s_addc_u32 s3, s3, 0
	global_load_dword v3, v1, s[2:3]
	s_add_u32 s2, s2, 0x2000
	s_addc_u32 s3, s3, 0
	global_load_dword v3, v1, s[2:3]
.Lipf1:
	s_or_b64 exec, exec, s[8:9]
	v_cmp_eq_u32_e32 vcc, 0, v0
	s_and_saveexec_b64 s[0:1], vcc
	s_cbranch_execz .LBB0_161
	v_readlane_b32 s2, v253, 3
	s_waitcnt vmcnt(0) expcnt(0) lgkmcnt(0)
	s_nop 0
	v_mov_b32_e32 v1, s2
	ds_read_b32 v3, v1
	ds_read_b32 v1, v1 offset:4
	s_waitcnt lgkmcnt(1)
	v_cmp_ne_u32_e32 vcc, 0, v3
	s_cbranch_vccnz .LBB0_129
	v_readlane_b32 s6, v253, 0
	v_readlane_b32 s7, v253, 1
	s_load_dwordx2 s[2:3], s[6:7], 0x4
	s_add_u32 s6, s44, 0x1200
	s_addc_u32 s7, s45, 0
	s_add_u32 s8, s44, 0x1400
	s_addc_u32 s9, s45, 0
	s_add_u32 s10, s44, 0x1500
	s_addc_u32 s11, s45, 0
	s_add_u32 s12, s44, 0x1600
	s_addc_u32 s13, s45, 0
	s_add_u32 s14, s44, 0x1700
	s_addc_u32 s15, s45, 0
	s_add_u32 s16, s44, 0x1800
	s_addc_u32 s17, s45, 0
	s_add_u32 s18, s44, 0x1900
	s_addc_u32 s19, s45, 0
	s_add_u32 s20, s44, 0x1a00
	s_addc_u32 s21, s45, 0
	s_add_u32 s22, s44, 0x1b00
	s_addc_u32 s23, s45, 0
	s_add_u32 s24, s44, 0x1c00
	s_addc_u32 s25, s45, 0
	s_add_u32 s26, s44, 0x1d00
	s_addc_u32 s27, s45, 0
	s_add_u32 s28, s44, 0x1e00
	s_addc_u32 s29, s45, 0
	s_add_u32 s30, s44, 0x1f00
	s_addc_u32 s31, s45, 0
	s_add_u32 s34, s44, 0x2000
	s_addc_u32 s35, s45, 0
	s_add_u32 s36, s44, 0x2100
	s_addc_u32 s37, s45, 0
	s_add_u32 s38, s44, 0x2200
	s_addc_u32 s39, s45, 0
	s_waitcnt lgkmcnt(0)
	s_mul_i32 s2, s2, s96
	s_add_u32 s40, s44, 0x2300
	s_mul_i32 s2, s2, s3
	s_addc_u32 s41, s45, 0
	s_mov_b32 s3, 1
	v_mov_b32_e32 v17, 0
	s_branch .LBB0_117

.LBB0_706:
	s_cmp_gt_i32 s95, 3
	s_cselect_b64 s[0:1], -1, 0
	s_and_b64 s[2:3], s[48:49], s[0:1]
	v_readlane_b32 s80, v253, 21
	s_andn2_b64 vcc, exec, s[2:3]
	v_readlane_b32 s81, v253, 22
	v_readlane_b32 s82, v253, 3
	v_readlane_b32 s60, v253, 36
	s_cbranch_vccnz .LBB0_756
	s_waitcnt vmcnt(0)
	v_cmp_eq_u32_e32 vcc, 0, v0
	s_waitcnt vmcnt(63) expcnt(7) lgkmcnt(15)
	s_barrier
	v_lshrrev_b32_e32 v1, 6, v0
	v_and_b32_e32 v2, 63, v0
	v_cmp_eq_u32_e32 vcc, 5, v1
	s_and_saveexec_b64 s[8:9], vcc
	s_cbranch_execz .Lipf2
	s_getpc_b64 s[2:3]
	v_lshlrev_b32_e32 v1, 7, v2
	global_load_dword v3, v1, s[2:3]
	s_add_u32 s2, s2, 0x2000
	s_addc_u32 s3, s3, 0
	global_load_dword v3, v1, s[2:3]
	s_add_u32 s2, s2, 0x2000
	s_addc_u32 s3, s3, 0
	global_load_dword v3, v1, s[2:3]
	s_add_u32 s2, s2, 0x2000
	s_addc_u32 s3, s3, 0
	global_load_dword v3, v1, s[2:3]
	s_add_u32 s2, s2, 0x2000
	s_addc_u32 s3, s3, 0
	global_load_dword v3, v1, s[2:3]
	s_add_u32 s2, s2, 0x2000
	s_addc_u32 s3, s3, 0
	global_load_dword v3, v1, s[2:3]
	s_add_u32 s2, s2, 0x2000
	s_addc_u32 s3, s3, 0
	global_load_dword v3, v1, s[2:3]
	s_add_u32 s2, s2, 0x2000
	s_addc_u32 s3, s3, 0
	global_load_dword v3, v1, s[2:3]
.Lipf2:
	s_or_b64 exec, exec, s[8:9]
	v_cmp_eq_u32_e32 vcc, 0, v0
	s_and_saveexec_b64 s[4:5], vcc
	s_cbranch_execz .LBB0_755
	v_mov_b32_e32 v1, s82
	s_waitcnt vmcnt(0) expcnt(0) lgkmcnt(0)
	ds_read_b32 v3, v1
	ds_read_b32 v1, v1 offset:4
	s_waitcnt lgkmcnt(1)
	v_cmp_ne_u32_e32 vcc, 0, v3
	s_cbranch_vccnz .LBB0_723
	v_readlane_b32 s6, v253, 0
	v_readlane_b32 s7, v253, 1
	s_load_dwordx2 s[2:3], s[6:7], 0x4
	s_add_u32 s6, s44, 0x1200
	s_addc_u32 s7, s45, 0
	s_add_u32 s8, s44, 0x1400
	s_addc_u32 s9, s45, 0
	s_add_u32 s10, s44, 0x1500
	s_addc_u32 s11, s45, 0
	s_add_u32 s12, s44, 0x1600
	s_addc_u32 s13, s45, 0
	s_add_u32 s14, s44, 0x1700
	s_addc_u32 s15, s45, 0
	s_add_u32 s16, s44, 0x1800
	s_addc_u32 s17, s45, 0
	s_add_u32 s18, s44, 0x1900
	s_addc_u32 s19, s45, 0
	s_add_u32 s20, s44, 0x1a00
	s_addc_u32 s21, s45, 0
	s_add_u32 s22, s44, 0x1b00
	s_addc_u32 s23, s45, 0
	s_add_u32 s28, s44, 0x1c00
	s_addc_u32 s29, s45, 0
	s_add_u32 s30, s44, 0x1d00
	s_addc_u32 s31, s45, 0
	s_add_u32 s40, s44, 0x1e00
	s_addc_u32 s41, s45, 0
	s_add_u32 s42, s44, 0x1f00
	s_addc_u32 s43, s45, 0
	s_add_u32 s46, s44, 0x2000
	s_addc_u32 s47, s45, 0
	s_add_u32 s48, s44, 0x2100
	s_addc_u32 s49, s45, 0
	s_add_u32 s50, s44, 0x2200
	s_addc_u32 s51, s45, 0
	s_waitcnt lgkmcnt(0)
	s_mul_i32 s2, s2, s96
	s_add_u32 s52, s44, 0x2300
	s_mov_b32 s35, s56
	s_mov_b32 s34, s55
	s_mul_i32 s2, s2, s3
	s_addc_u32 s53, s45, 0
	s_mov_b32 s3, 1
	v_mov_b32_e32 v17, 0
	s_branch .LBB0_711

.LBB0_874:
	s_cmp_gt_i32 s95, 4
	s_cselect_b64 s[0:1], -1, 0
	s_and_b64 s[2:3], s[4:5], s[0:1]
	s_andn2_b64 vcc, exec, s[2:3]
	s_cbranch_vccnz .LBB0_924
	s_waitcnt vmcnt(0)
	v_cmp_eq_u32_e32 vcc, 0, v0
	s_waitcnt vmcnt(63) expcnt(7) lgkmcnt(15)
	s_barrier
	v_lshrrev_b32_e32 v1, 6, v0
	v_and_b32_e32 v2, 63, v0
	v_cmp_eq_u32_e32 vcc, 5, v1
	s_and_saveexec_b64 s[8:9], vcc
	s_cbranch_execz .Lipf3
	s_getpc_b64 s[2:3]
	v_lshlrev_b32_e32 v1, 7, v2
	global_load_dword v3, v1, s[2:3]
	s_add_u32 s2, s2, 0x2000
	s_addc_u32 s3, s3, 0
	global_load_dword v3, v1, s[2:3]
	s_add_u32 s2, s2, 0x2000
	s_addc_u32 s3, s3, 0
	global_load_dword v3, v1, s[2:3]
	s_add_u32 s2, s2, 0x2000
	s_addc_u32 s3, s3, 0
	global_load_dword v3, v1, s[2:3]
	s_add_u32 s2, s2, 0x2000
	s_addc_u32 s3, s3, 0
	global_load_dword v3, v1, s[2:3]
.Lipf3:
	s_or_b64 exec, exec, s[8:9]
	v_cmp_eq_u32_e32 vcc, 0, v0
	v_lshrrev_b32_e32 v1, 6, v0
	v_and_b32_e32 v2, 63, v0
	v_add_u32_e32 v4, -1, v1
	v_cmp_gt_u32_e32 vcc, 1, v4
	s_and_saveexec_b64 s[8:9], vcc
	s_cbranch_execz .Lwpf3
	v_readlane_b32 s2, v253, 20
	s_nop 3
	s_mul_i32 s2, s2, 1
	v_add_u32_e32 v1, s2, v4
	v_mul_u32_u24_e32 v1, 0x2000, v1
	v_lshl_add_u32 v1, v2, 7, v1
	s_add_u32 s2, s44, 0xa00000
	s_addc_u32 s3, s45, 0
	global_load_dword v3, v1, s[2:3]

.LBB0_1081:
	s_cmp_gt_i32 s95, 5
	s_cselect_b64 s[0:1], -1, 0
	s_and_b64 s[2:3], s[4:5], s[0:1]
	s_andn2_b64 vcc, exec, s[2:3]
	s_cbranch_vccnz .LBB0_1131
	s_waitcnt vmcnt(0)
	v_cmp_eq_u32_e32 vcc, 0, v0
	s_waitcnt vmcnt(63) expcnt(7) lgkmcnt(15)
	s_barrier
	v_lshrrev_b32_e32 v1, 6, v0
	v_and_b32_e32 v2, 63, v0
	v_cmp_eq_u32_e32 vcc, 5, v1
	s_and_saveexec_b64 s[8:9], vcc
	s_cbranch_execz .Lipf4
	s_getpc_b64 s[2:3]
	v_lshlrev_b32_e32 v1, 7, v2
	global_load_dword v3, v1, s[2:3]
	s_add_u32 s2, s2, 0x2000
	s_addc_u32 s3, s3, 0
	global_load_dword v3, v1, s[2:3]
	s_add_u32 s2, s2, 0x2000
	s_addc_u32 s3, s3, 0
	global_load_dword v3, v1, s[2:3]
.Lipf4:
	s_or_b64 exec, exec, s[8:9]
	v_cmp_eq_u32_e32 vcc, 0, v0
	v_lshrrev_b32_e32 v1, 6, v0
	v_and_b32_e32 v2, 63, v0
	v_add_u32_e32 v4, -1, v1
	v_cmp_gt_u32_e32 vcc, 1, v4
	s_and_saveexec_b64 s[8:9], vcc
	s_cbranch_execz .Lwpf4
	v_readlane_b32 s2, v253, 20
	s_nop 3
	s_mul_i32 s2, s2, 1
	v_add_u32_e32 v1, s2, v4
	v_mul_u32_u24_e32 v1, 0x2000, v1
	v_lshl_add_u32 v1, v2, 7, v1
	s_add_u32 s2, s44, 0xc00000
	s_addc_u32 s3, s45, 0
	global_load_dword v3, v1, s[2:3]

.LBB0_1175:
	s_cmp_gt_i32 s95, 6
	s_cselect_b64 s[0:1], -1, 0
	s_and_b64 s[2:3], s[6:7], s[0:1]
	s_andn2_b64 vcc, exec, s[2:3]
	s_cbranch_vccnz .LBB0_1225
	s_waitcnt vmcnt(0)
	v_cmp_eq_u32_e32 vcc, 0, v0
	s_waitcnt lgkmcnt(0)
	s_barrier
	v_lshrrev_b32_e32 v1, 6, v0
	v_and_b32_e32 v2, 63, v0
	v_cmp_eq_u32_e32 vcc, 5, v1
	s_and_saveexec_b64 s[8:9], vcc
	s_cbranch_execz .Lipf5
	s_getpc_b64 s[2:3]
	v_lshlrev_b32_e32 v1, 7, v2
	global_load_dword v3, v1, s[2:3]
	s_add_u32 s2, s2, 0x2000
	s_addc_u32 s3, s3, 0
	global_load_dword v3, v1, s[2:3]
.Lipf5:
	s_or_b64 exec, exec, s[8:9]
	v_cmp_eq_u32_e32 vcc, 0, v0
	v_lshrrev_b32_e32 v1, 6, v0
	v_and_b32_e32 v2, 63, v0
	v_add_u32_e32 v4, -1, v1
	v_cmp_gt_u32_e32 vcc, 4, v4
	s_and_saveexec_b64 s[8:9], vcc
	s_cbranch_execz .Lwpf5
	v_readlane_b32 s2, v253, 20
	s_nop 3
	s_mul_i32 s2, s2, 4
	v_add_u32_e32 v1, s2, v4
	v_mul_u32_u24_e32 v1, 0x8000, v1
	v_lshl_add_u32 v1, v2, 7, v1
	s_add_u32 s2, s44, 0x1d600000
	s_addc_u32 s3, s45, 0
	global_load_dword v3, v1, s[2:3]
	s_add_u32 s2, s2, 0x2000
	s_addc_u32 s3, s3, 0
	global_load_dword v3, v1, s[2:3]
	s_add_u32 s2, s2, 0x2000
	s_addc_u32 s3, s3, 0
	global_load_dword v3, v1, s[2:3]
	s_add_u32 s2, s2, 0x2000
	s_addc_u32 s3, s3, 0
	global_load_dword v3, v1, s[2:3]

.LBB0_1251:
	s_cmp_gt_i32 s95, 7
	s_cselect_b64 s[4:5], -1, 0
	s_and_b64 s[0:1], s[0:1], s[4:5]
	s_andn2_b64 vcc, exec, s[0:1]
	s_cbranch_vccnz .LBB0_1301
	s_waitcnt vmcnt(0)
	v_cmp_eq_u32_e32 vcc, 0, v0
	s_waitcnt lgkmcnt(0)
	s_barrier
	v_lshrrev_b32_e32 v1, 6, v0
	v_and_b32_e32 v2, 63, v0
	v_cmp_eq_u32_e32 vcc, 5, v1
	s_and_saveexec_b64 s[8:9], vcc
	s_cbranch_execz .Lipf6
	s_getpc_b64 s[2:3]
	v_lshlrev_b32_e32 v1, 7, v2
	global_load_dword v3, v1, s[2:3]
.Lipf6:
	s_or_b64 exec, exec, s[8:9]
	v_cmp_eq_u32_e32 vcc, 0, v0
	v_lshrrev_b32_e32 v1, 6, v0
	v_and_b32_e32 v2, 63, v0
	v_add_u32_e32 v4, -1, v1
	v_cmp_gt_u32_e32 vcc, 4, v4
	s_and_saveexec_b64 s[8:9], vcc
	s_cbranch_execz .Lwpf6
	v_readlane_b32 s2, v253, 20
	s_nop 3
	s_mul_i32 s2, s2, 4
	v_add_u32_e32 v1, s2, v4
	v_mul_u32_u24_e32 v1, 0x2000, v1
	v_lshl_add_u32 v1, v2, 7, v1
	s_add_u32 s2, s44, 0x1600000
	s_addc_u32 s3, s45, 0
	global_load_dword v3, v1, s[2:3]
